# selection ranking: the importance set-up (forced/validity adjust) is also split across the head-pair waves, each wave writes its four groups into both waves' rows
# speedup vs baseline: 1.0149x; 1.0050x over previous
; #define LAS __attribute__((address_space(3)))
; DI void attn_phase(const Params& p, const int layer, const int wid_s) {
;     ...
; #pragma unroll
;         for (int dt = 0; dt < 4; ++dt)
; #pragma unroll
;           for (int j = 0; j < 4; ++j) fin[(hp * 16 + dt * 4 + j) * 64] = o[dt][j] * gate_c;
;       }
;       unsigned mk = (2u << cur) - 1u;
;       if (cur >= 8) {
;       float impv[8];
;       __syncthreads();
; #pragma unroll
;       for (int nt = 0; nt < 8; ++nt) {
;         const float mine = impx[(wave * 8 + nt) * 64], other = impx[((wave ^ 4) * 8 + nt) * 64];
;         const float im = hpair == 0 ? mine + other : other + mine;
;         const int jb = nt * 4 + fql;
;         const bool forced = (jb == 0) || (jb == cur) || (jb == cur - 1);
;         impv[nt] = jb <= cur ? im + (forced ? 1e6f : 0.f) : NEGF;
;         impb[jb] = impv[nt];
;       }
;       __syncthreads();
;       int cnt[8];
; #pragma unroll
;       for (int nt = 0; nt < 8; ++nt) cnt[nt] = 0;
; #pragma unroll
;       for (int i = 0; i < 8; ++i) {
;         const f32x4 r4 = *(const LAS f32x4*)(impb + 4 * i);
.LBB0_332:
	v_cvt_f32_f16_sdwa v0, v121 dst_sel:DWORD dst_unused:UNUSED_PAD src0_sel:WORD_1
	v_mul_f32_e32 v0, 0xbfb8aa3b, v0
	v_exp_f32_e32 v0, v0
	s_nop 0
	v_add_f32_e32 v0, 1.0, v0
	v_div_scale_f32 v2, s[4:5], v0, v0, 1.0
	v_rcp_f32_e32 v3, v2
	v_div_scale_f32 v5, vcc, 1.0, v0, 1.0
	s_lshl_b32 s4, 2, s54
	v_fma_f32 v6, -v2, v3, 1.0
	v_fmac_f32_e32 v3, v6, v3
	v_mul_f32_e32 v6, v5, v3
	v_fma_f32 v7, -v2, v6, v5
	v_fmac_f32_e32 v6, v7, v3
	v_fma_f32 v2, -v2, v6, v5
	v_div_fmas_f32 v2, v2, v3, v6
	v_div_fixup_f32 v0, v2, v0, 1.0
	v_mul_f32_e32 v2, v0, v36
	v_mul_f32_e32 v3, v0, v37
	v_mul_f32_e32 v5, v0, v38
	v_mul_f32_e32 v6, v0, v39
	v_mul_f32_e32 v7, v0, v28
	ds_write2st64_b32 v188, v2, v3 offset0:168 offset1:169
	ds_write2st64_b32 v188, v5, v6 offset0:170 offset1:171
	v_mul_f32_e32 v2, v0, v29
	ds_write2st64_b32 v188, v7, v2 offset0:172 offset1:173
	v_mul_f32_e32 v2, v0, v30
	v_mul_f32_e32 v3, v0, v31
	ds_write2st64_b32 v188, v2, v3 offset0:174 offset1:175
	v_mul_f32_e32 v2, v0, v32
	v_mul_f32_e32 v3, v0, v33
	ds_write2st64_b32 v188, v2, v3 offset0:176 offset1:177
	v_mul_f32_e32 v2, v0, v34
	v_mul_f32_e32 v3, v0, v35
	ds_write2st64_b32 v188, v2, v3 offset0:178 offset1:179
	v_mul_f32_e32 v2, v0, v24
	v_mul_f32_e32 v3, v0, v25
	s_add_i32 s4, s4, -1
	ds_write2st64_b32 v188, v2, v3 offset0:180 offset1:181
	v_mul_f32_e32 v2, v0, v26
	v_mul_f32_e32 v0, v0, v27
	s_and_b64 vcc, exec, s[0:1]
	v_mov_b32_e32 v5, s4
	ds_write2st64_b32 v188, v2, v0 offset0:182 offset1:183
	s_cbranch_vccnz .LBB0_334
	s_waitcnt lgkmcnt(0)
	s_barrier
	s_add_i32 s6, s54, -1
	v_lshl_add_u32 v24, v123, 2, v147
	s_and_b64 vcc, exec, s[30:31]
	s_movk_i32 s7, 0x2400
	s_cselect_b32 s7, 0xffffdc00, s7
	v_add_u32_e32 v25, s7, v24
	s_cbranch_vccz .Lrk_lo
	ds_read_b32 v202, v151 offset:23680
	ds_read_b32 v210, v182 offset:23680
	ds_read_b32 v203, v151 offset:23936
	ds_read_b32 v211, v182 offset:23936
	ds_read_b32 v204, v151 offset:24192
	ds_read_b32 v212, v182 offset:24192
	ds_read_b32 v205, v151 offset:24448
	ds_read_b32 v213, v182 offset:24448
	v_add_u32_e32 v242, 16, v123
	v_add_u32_e32 v243, 20, v123
	v_add_u32_e32 v244, 24, v123
	v_add_u32_e32 v245, 28, v123
	s_waitcnt lgkmcnt(0)
	s_cmp_gt_i32 s54, 15
	s_cbranch_scc1 .Lrk_pd_h4
	ds_write_b32 v24, v4 offset:4288
	ds_write_b32 v25, v4 offset:4288
	s_branch .Lrk_ps_h4
.Lrk_pd_h4:
	v_cmp_eq_u32_e64 s[8:9], 0, v242
	v_cmp_eq_u32_e64 s[10:11], s54, v242
	v_cmp_eq_u32_e64 s[12:13], s6, v242
	v_add_f32_e32 v202, v202, v210
	s_or_b64 s[8:9], s[8:9], s[10:11]
	s_or_b64 s[8:9], s[8:9], s[12:13]
	v_cmp_lt_i32_e64 s[14:15], s54, v242
	s_nop 0
	v_cndmask_b32_e64 v0, 0, v159, s[8:9]
	s_nop 0
	v_add_f32_e32 v202, v0, v202
	v_cndmask_b32_e64 v36, v202, v4, s[14:15]
	ds_write_b32 v24, v36 offset:4288
	ds_write_b32 v25, v36 offset:4288
.Lrk_ps_h4:
	s_cmp_gt_i32 s54, 19
	s_cbranch_scc1 .Lrk_pd_h5
	ds_write_b32 v24, v4 offset:4304
	ds_write_b32 v25, v4 offset:4304
	s_branch .Lrk_ps_h5
.Lrk_pd_h5:
	v_cmp_eq_u32_e64 s[8:9], 0, v243
	v_cmp_eq_u32_e64 s[10:11], s54, v243
	v_cmp_eq_u32_e64 s[12:13], s6, v243
	v_add_f32_e32 v203, v203, v211
	s_or_b64 s[8:9], s[8:9], s[10:11]
	s_or_b64 s[8:9], s[8:9], s[12:13]
	v_cmp_lt_i32_e64 s[14:15], s54, v243
	s_nop 0
	v_cndmask_b32_e64 v0, 0, v159, s[8:9]
	s_nop 0
	v_add_f32_e32 v203, v0, v203
	v_cndmask_b32_e64 v35, v203, v4, s[14:15]
	ds_write_b32 v24, v35 offset:4304
	ds_write_b32 v25, v35 offset:4304
.Lrk_ps_h5:
	s_cmp_gt_i32 s54, 23
	s_cbranch_scc1 .Lrk_pd_h6
	ds_write_b32 v24, v4 offset:4320
	ds_write_b32 v25, v4 offset:4320
	s_branch .Lrk_ps_h6
.Lrk_pd_h6:
	v_cmp_eq_u32_e64 s[8:9], 0, v244
	v_cmp_eq_u32_e64 s[10:11], s54, v244
	v_cmp_eq_u32_e64 s[12:13], s6, v244
	v_add_f32_e32 v204, v204, v212
	s_or_b64 s[8:9], s[8:9], s[10:11]
	s_or_b64 s[8:9], s[8:9], s[12:13]
	v_cmp_lt_i32_e64 s[14:15], s54, v244
	s_nop 0
	v_cndmask_b32_e64 v0, 0, v159, s[8:9]
	s_nop 0
	v_add_f32_e32 v204, v0, v204
	v_cndmask_b32_e64 v34, v204, v4, s[14:15]
	ds_write_b32 v24, v34 offset:4320
	ds_write_b32 v25, v34 offset:4320
.Lrk_ps_h6:
	s_cmp_gt_i32 s54, 27
	s_cbranch_scc1 .Lrk_pd_h7
	ds_write_b32 v24, v4 offset:4336
	ds_write_b32 v25, v4 offset:4336
	s_branch .Lrk_ps_h7
.Lrk_pd_h7:
	v_cmp_eq_u32_e64 s[8:9], 0, v245
	v_cmp_eq_u32_e64 s[10:11], s54, v245
	v_cmp_eq_u32_e64 s[12:13], s6, v245
	v_add_f32_e32 v205, v205, v213
	s_or_b64 s[8:9], s[8:9], s[10:11]
	s_or_b64 s[8:9], s[8:9], s[12:13]
	v_cmp_lt_i32_e64 s[14:15], s54, v245
	s_nop 0
	v_cndmask_b32_e64 v0, 0, v159, s[8:9]
	s_nop 0
	v_add_f32_e32 v205, v0, v205
	v_cndmask_b32_e64 v33, v205, v4, s[14:15]
	ds_write_b32 v24, v33 offset:4336
	ds_write_b32 v25, v33 offset:4336
.Lrk_ps_h7:
	s_waitcnt lgkmcnt(0)
	s_barrier
	ds_read_b128 v[198:201], v147 offset:4224
	ds_read_b128 v[202:205], v147 offset:4240
	ds_read_b128 v[206:209], v147 offset:4256
	ds_read_b128 v[210:213], v147 offset:4272
	ds_read_b128 v[214:217], v147 offset:4288
	ds_read_b128 v[218:221], v147 offset:4304
	ds_read_b128 v[222:225], v147 offset:4320
	ds_read_b128 v[226:229], v147 offset:4336
	v_cmp_lt_i32_e64 s[6:7], 0, v123
	v_cmp_lt_i32_e64 s[8:9], 1, v123
	v_cmp_lt_i32_e64 s[10:11], 2, v123
	v_mov_b32_e32 v234, 0
	v_mov_b32_e32 v235, 0
	v_mov_b32_e32 v236, 0
	v_mov_b32_e32 v237, 0
	s_waitcnt lgkmcnt(0)
	s_cmp_gt_i32 s54, 15
	s_cbranch_scc1 .Lrk_do_h4
	v_mov_b32_e32 v242, 0
	s_branch .Lrk_sk_h4

; #define LAS __attribute__((address_space(3)))
; DI void attn_phase(const Params& p, const int layer, const int wid_s) {
;     ...
; #pragma unroll
;       for (int nt = 0; nt < 8; ++nt) {
;         const float mine = impx[(wave * 8 + nt) * 64], other = impx[((wave ^ 4) * 8 + nt) * 64];
;         const float im = hpair == 0 ? mine + other : other + mine;
;         const int jb = nt * 4 + fql;
;         const bool forced = (jb == 0) || (jb == cur) || (jb == cur - 1);
;         impv[nt] = jb <= cur ? im + (forced ? 1e6f : 0.f) : NEGF;
;         impb[jb] = impv[nt];
;       }
;       __syncthreads();
;       int cnt[8];
; #pragma unroll
;       for (int nt = 0; nt < 8; ++nt) cnt[nt] = 0;
; #pragma unroll
;       for (int i = 0; i < 8; ++i) {
;         const f32x4 r4 = *(const LAS f32x4*)(impb + 4 * i);
.Lrk_lo:
	ds_read_b32 v198, v151 offset:22656
	ds_read_b32 v206, v182 offset:22656
	ds_read_b32 v199, v151 offset:22912
	ds_read_b32 v207, v182 offset:22912
	ds_read_b32 v200, v151 offset:23168
	ds_read_b32 v208, v182 offset:23168
	ds_read_b32 v201, v151 offset:23424
	ds_read_b32 v209, v182 offset:23424
	v_add_u32_e32 v238, 0, v123
	v_add_u32_e32 v239, 4, v123
	v_add_u32_e32 v240, 8, v123
	v_add_u32_e32 v241, 12, v123
	s_waitcnt lgkmcnt(0)
	v_cmp_eq_u32_e64 s[8:9], 0, v238
	v_cmp_eq_u32_e64 s[10:11], s54, v238
	v_cmp_eq_u32_e64 s[12:13], s6, v238
	v_add_f32_e32 v198, v198, v206
	s_or_b64 s[8:9], s[8:9], s[10:11]
	s_or_b64 s[8:9], s[8:9], s[12:13]
	v_cmp_lt_i32_e64 s[14:15], s54, v238
	s_nop 0
	v_cndmask_b32_e64 v0, 0, v159, s[8:9]
	s_nop 0
	v_add_f32_e32 v198, v0, v198
	v_cndmask_b32_e64 v39, v198, v4, s[14:15]
	ds_write_b32 v24, v39 offset:4224
	ds_write_b32 v25, v39 offset:4224
	s_cmp_gt_i32 s54, 3
	s_cbranch_scc1 .Lrk_pd_l1
	ds_write_b32 v24, v4 offset:4240
	ds_write_b32 v25, v4 offset:4240
	s_branch .Lrk_ps_l1
.Lrk_pd_l1:
	v_cmp_eq_u32_e64 s[8:9], 0, v239
	v_cmp_eq_u32_e64 s[10:11], s54, v239
	v_cmp_eq_u32_e64 s[12:13], s6, v239
	v_add_f32_e32 v199, v199, v207
	s_or_b64 s[8:9], s[8:9], s[10:11]
	s_or_b64 s[8:9], s[8:9], s[12:13]
	v_cmp_lt_i32_e64 s[14:15], s54, v239
	s_nop 0
	v_cndmask_b32_e64 v0, 0, v159, s[8:9]
	s_nop 0
	v_add_f32_e32 v199, v0, v199
	v_cndmask_b32_e64 v40, v199, v4, s[14:15]
	ds_write_b32 v24, v40 offset:4240
	ds_write_b32 v25, v40 offset:4240
.Lrk_ps_l1:
	s_cmp_gt_i32 s54, 7
	s_cbranch_scc1 .Lrk_pd_l2
	ds_write_b32 v24, v4 offset:4256
	ds_write_b32 v25, v4 offset:4256
	s_branch .Lrk_ps_l2
.Lrk_pd_l2:
	v_cmp_eq_u32_e64 s[8:9], 0, v240
	v_cmp_eq_u32_e64 s[10:11], s54, v240
	v_cmp_eq_u32_e64 s[12:13], s6, v240
	v_add_f32_e32 v200, v200, v208
	s_or_b64 s[8:9], s[8:9], s[10:11]
	s_or_b64 s[8:9], s[8:9], s[12:13]
	v_cmp_lt_i32_e64 s[14:15], s54, v240
	s_nop 0
	v_cndmask_b32_e64 v0, 0, v159, s[8:9]
	s_nop 0
	v_add_f32_e32 v200, v0, v200
	v_cndmask_b32_e64 v38, v200, v4, s[14:15]
	ds_write_b32 v24, v38 offset:4256
	ds_write_b32 v25, v38 offset:4256
.Lrk_ps_l2:
	s_cmp_gt_i32 s54, 11
	s_cbranch_scc1 .Lrk_pd_l3
	ds_write_b32 v24, v4 offset:4272
	ds_write_b32 v25, v4 offset:4272
	s_branch .Lrk_ps_l3
.Lrk_pd_l3:
	v_cmp_eq_u32_e64 s[8:9], 0, v241
	v_cmp_eq_u32_e64 s[10:11], s54, v241
	v_cmp_eq_u32_e64 s[12:13], s6, v241
	v_add_f32_e32 v201, v201, v209
	s_or_b64 s[8:9], s[8:9], s[10:11]
	s_or_b64 s[8:9], s[8:9], s[12:13]
	v_cmp_lt_i32_e64 s[14:15], s54, v241
	s_nop 0
	v_cndmask_b32_e64 v0, 0, v159, s[8:9]
	s_nop 0
	v_add_f32_e32 v201, v0, v201
	v_cndmask_b32_e64 v37, v201, v4, s[14:15]
	ds_write_b32 v24, v37 offset:4272
	ds_write_b32 v25, v37 offset:4272
.Lrk_ps_l3:
	s_waitcnt lgkmcnt(0)
	s_barrier
	ds_read_b128 v[198:201], v147 offset:4224
	ds_read_b128 v[202:205], v147 offset:4240
	ds_read_b128 v[206:209], v147 offset:4256
	ds_read_b128 v[210:213], v147 offset:4272
	ds_read_b128 v[214:217], v147 offset:4288
	ds_read_b128 v[218:221], v147 offset:4304
	ds_read_b128 v[222:225], v147 offset:4320
	ds_read_b128 v[226:229], v147 offset:4336
	v_cmp_lt_i32_e64 s[6:7], 0, v123
	v_cmp_lt_i32_e64 s[8:9], 1, v123
	v_cmp_lt_i32_e64 s[10:11], 2, v123
	v_mov_b32_e32 v230, 0
	v_mov_b32_e32 v231, 0
	v_mov_b32_e32 v232, 0
	v_mov_b32_e32 v233, 0
	s_waitcnt lgkmcnt(0)
	s_cmp_gt_i32 s54, -1
	s_cbranch_scc1 .Lrk_do_l0
	v_mov_b32_e32 v238, 0
	s_branch .Lrk_sk_l0
